# plus XR branches on scalar tests, mask derivation behind the barrier
# baseline (speedup 1.0000x reference)
; #define PG8_LDX(b) do { if constexpr (XR) { _Pragma("unroll") for (int k = 0; k < 2; ++k) Ax_[k] = *(const PG8_LAS bf16x8*)(lds + XR_OFF + (b) * 2048 + aoffx + k * 1024); } } while (0)
; #define PG8_MMAX() do { if constexpr (XR) { if (hasx) { __builtin_amdgcn_s_setprio(1); if (wr == 0) PG8_MMAX_(B0); else PG8_MMAX_(B1); __builtin_amdgcn_s_setprio(0); } } } while (0)
; #define PG8_WAIT_LOOP() do { if constexpr (XR) PG8_WAIT_V(9); else PG8_WAIT_V(8); } while (0)
; #define PG8_STAGE(bufoff, gbase, voff) do { _Pragma("unroll") for (int _i = 0; _i < 2; ++_i) \
;         __builtin_amdgcn_global_load_lds((const unsigned*)((const char*)(gbase) + (voff)[_i]), (PG8_LAS unsigned*)(lds + (bufoff) + ldsw + _i * 8192), 16, 0, 0); } while (0)
; #define PG8_LDA(dst, b, h) do { _Pragma("unroll") for (int m = 0; m < 4; ++m) _Pragma("unroll") for (int k = 0; k < 2; ++k) dst[m][k] = *(const PG8_LAS bf16x8*)(lds + PG8_SA(b, h) + aoff + m * 2048 + k * 1024); } while (0)
; #define PG8_LDB(dst, b, h) do { _Pragma("unroll") for (int n = 0; n < 2; ++n) _Pragma("unroll") for (int k = 0; k < 2; ++k) dst[n][k] = *(const PG8_LAS bf16x8*)(lds + PG8_SB(b, h) + boff + n * 2048 + k * 1024); } while (0)
; #define PG8_MMA(ai, bj, At, Bt) do { __builtin_amdgcn_s_setprio(1); _Pragma("unroll") for (int m = 0; m < 4; ++m) _Pragma("unroll") for (int n = 0; n < 2; ++n) _Pragma("unroll") for (int k = 0; k < 2; ++k) \
;         acc[ai][bj][m][n] = __builtin_amdgcn_mfma_f32_16x16x32_bf16(Bt[n][k], At[m][k], acc[ai][bj][m][n], 0, 0, 0); __builtin_amdgcn_s_setprio(0); } while (0)
; #define PG8_WAIT_L(n) asm volatile("s_waitcnt lgkmcnt(" #n ")" ::: "memory")
; #define PG8_BAR __builtin_amdgcn_s_barrier()
; #define PG8_SCHED __builtin_amdgcn_sched_barrier(0)
; template <class Epi, class Sched, bool ALIGN_EPI = false, bool SP2 = false, bool DRAIN = true, bool XR = false>
; __device__ __forceinline__ void gemm_phase(PG8_LAS unsigned char* lds, const Gemm g, const Sched& S, const Epi& E) {
;     ...
;             PG8_LDB(B0, 0, 0); PG8_LDB(B1, 0, 1); PG8_SCHED; PG8_LDA(At, 0, 0); PG8_LDX(0); PG8_STAGE(PG8_SA(1, 1), a1 + hstepA, voffA);
;             PG8_WAIT_LOOP(); PG8_WAIT_L(0); PG8_BAR; PG8_MMA(0, 0, At, B0); PG8_MMA(0, 1, At, B1); PG8_MMAX(); PG8_BAR; PG8_SCHED;
.LBB0_1220:
	v_add_u32_e32 v4, 0x10000, v250
	ds_read_b128 v[158:161], v4
	ds_read_b128 v[162:165], v4 offset:1024
	ds_read_b128 v[166:169], v4 offset:2048
	ds_read_b128 v[170:173], v4 offset:3072
	v_add_u32_e32 v4, 0x14000, v250
	s_and_b32 s8, s50, s82
	ds_read_b128 v[142:145], v4
	ds_read_b128 v[146:149], v4 offset:1024
	ds_read_b128 v[150:153], v4 offset:2048
	ds_read_b128 v[154:157], v4 offset:3072
	s_lshr_b32 s84, s8, 2
	s_lshl_b32 s8, s8, 7
	s_lshl_b64 s[6:7], s[84:85], 9
	s_and_b32 s8, s8, 0x100
	s_add_u32 s6, s18, s6
	s_addc_u32 s7, s19, s7
	s_add_u32 s6, s6, s8
	s_addc_u32 s7, s7, 0
	s_add_u32 s6, s6, s10
	v_add_u32_e32 v4, 0x22400, v240
	s_addc_u32 s7, s7, s11
	ds_read_b128 v[182:185], v251
	ds_read_b128 v[186:189], v251 offset:1024
	ds_read_b128 v[190:193], v251 offset:2048
	ds_read_b128 v[194:197], v251 offset:3072
	ds_read_b128 v[198:201], v251 offset:4096
	ds_read_b128 v[202:205], v251 offset:5120
	ds_read_b128 v[224:227], v251 offset:6144
	ds_read_b128 v[228:231], v251 offset:7168
	ds_read_b128 v[174:177], v4
	ds_read_b128 v[178:181], v4 offset:1024
	v_lshl_add_u64 v[4:5], s[6:7], 0, v[214:215]
	v_lshl_add_u64 v[4:5], v[4:5], 0, s[86:87]
	s_add_i32 m0, s64, 0xc000
	s_nop 0
	global_load_lds_dwordx4 v[4:5], off
	v_lshl_add_u64 v[4:5], s[6:7], 0, v[218:219]
	v_lshl_add_u64 v[4:5], v[4:5], 0, s[86:87]
	s_add_i32 m0, s64, 0xe000
	s_nop 0
	global_load_lds_dwordx4 v[4:5], off
	s_waitcnt vmcnt(9)
	s_waitcnt lgkmcnt(0)
	s_setprio 1
	s_barrier
	v_mfma_f32_16x16x32_bf16 v[138:141], v[158:161], v[182:185], v[138:141]
	v_mfma_f32_16x16x32_bf16 v[134:137], v[166:169], v[182:185], v[134:137]
	v_mfma_f32_16x16x32_bf16 v[130:133], v[158:161], v[190:193], v[130:133]
	v_mfma_f32_16x16x32_bf16 v[126:129], v[166:169], v[190:193], v[126:129]
	v_mfma_f32_16x16x32_bf16 v[122:125], v[158:161], v[198:201], v[122:125]
	v_mfma_f32_16x16x32_bf16 v[118:121], v[166:169], v[198:201], v[118:121]
	v_mfma_f32_16x16x32_bf16 v[114:117], v[158:161], v[224:227], v[114:117]
	v_mfma_f32_16x16x32_bf16 v[110:113], v[166:169], v[224:227], v[110:113]
	v_mfma_f32_16x16x32_bf16 v[138:141], v[162:165], v[186:189], v[138:141]
	v_mfma_f32_16x16x32_bf16 v[134:137], v[170:173], v[186:189], v[134:137]
	v_mfma_f32_16x16x32_bf16 v[130:133], v[162:165], v[194:197], v[130:133]
	v_mfma_f32_16x16x32_bf16 v[126:129], v[170:173], v[194:197], v[126:129]
	v_mfma_f32_16x16x32_bf16 v[122:125], v[162:165], v[202:205], v[122:125]
	v_mfma_f32_16x16x32_bf16 v[118:121], v[170:173], v[202:205], v[118:121]
	v_mfma_f32_16x16x32_bf16 v[114:117], v[162:165], v[228:231], v[114:117]
	v_mfma_f32_16x16x32_bf16 v[110:113], v[170:173], v[228:231], v[110:113]
	v_mfma_f32_16x16x32_bf16 v[106:109], v[142:145], v[182:185], v[106:109]
	v_mfma_f32_16x16x32_bf16 v[102:105], v[150:153], v[182:185], v[102:105]
	v_mfma_f32_16x16x32_bf16 v[98:101], v[142:145], v[190:193], v[98:101]
	v_mfma_f32_16x16x32_bf16 v[94:97], v[150:153], v[190:193], v[94:97]
	v_mfma_f32_16x16x32_bf16 v[90:93], v[142:145], v[198:201], v[90:93]
	v_mfma_f32_16x16x32_bf16 v[86:89], v[150:153], v[198:201], v[86:89]
	v_mfma_f32_16x16x32_bf16 v[82:85], v[142:145], v[224:227], v[82:85]
	v_mfma_f32_16x16x32_bf16 v[78:81], v[150:153], v[224:227], v[78:81]
	v_mfma_f32_16x16x32_bf16 v[106:109], v[146:149], v[186:189], v[106:109]
	v_mfma_f32_16x16x32_bf16 v[102:105], v[154:157], v[186:189], v[102:105]
	v_mfma_f32_16x16x32_bf16 v[98:101], v[146:149], v[194:197], v[98:101]
	v_mfma_f32_16x16x32_bf16 v[94:97], v[154:157], v[194:197], v[94:97]
	v_mfma_f32_16x16x32_bf16 v[90:93], v[146:149], v[202:205], v[90:93]
	v_mfma_f32_16x16x32_bf16 v[86:89], v[154:157], v[202:205], v[86:89]
	v_mfma_f32_16x16x32_bf16 v[82:85], v[146:149], v[228:231], v[82:85]
	v_mfma_f32_16x16x32_bf16 v[78:81], v[154:157], v[228:231], v[78:81]
	s_setprio 0
	s_cmp_eq_u64 s[22:23], 0
	s_cbranch_scc1 .LBB0_1226
	s_setprio 1
	s_mov_b64 s[48:49], -1
	s_cmp_eq_u64 s[40:41], 0
	s_cbranch_scc1 .LBB0_1223
	v_mfma_f32_16x16x32_bf16 v[10:13], v[142:145], v[174:177], v[10:13]
	s_mov_b64 s[48:49], 0
	v_mfma_f32_16x16x32_bf16 v[6:9], v[150:153], v[174:177], v[6:9]
	v_mfma_f32_16x16x32_bf16 v[10:13], v[146:149], v[178:181], v[10:13]
	v_mfma_f32_16x16x32_bf16 v[6:9], v[154:157], v[178:181], v[6:9]

; #define PG8_STAGEX(b, gbase) do { if constexpr (XR) { if (lane < 16) __builtin_amdgcn_global_load_lds((const unsigned*)((const char*)(gbase) + voffX), (PG8_LAS unsigned*)(lds + XR_OFF + (b) * 2048 + wid * 256), 16, 0, 0); } } while (0)
; #define PG8_LDX(b) do { if constexpr (XR) { _Pragma("unroll") for (int k = 0; k < 2; ++k) Ax_[k] = *(const PG8_LAS bf16x8*)(lds + XR_OFF + (b) * 2048 + aoffx + k * 1024); } } while (0)
; #define PG8_MMAX() do { if constexpr (XR) { if (hasx) { __builtin_amdgcn_s_setprio(1); if (wr == 0) PG8_MMAX_(B0); else PG8_MMAX_(B1); __builtin_amdgcn_s_setprio(0); } } } while (0)
; #define PG8_WAIT_LOOP() do { if constexpr (XR) PG8_WAIT_V(9); else PG8_WAIT_V(8); } while (0)
; #define PG8_STAGE(bufoff, gbase, voff) do { _Pragma("unroll") for (int _i = 0; _i < 2; ++_i) \
;         __builtin_amdgcn_global_load_lds((const unsigned*)((const char*)(gbase) + (voff)[_i]), (PG8_LAS unsigned*)(lds + (bufoff) + ldsw + _i * 8192), 16, 0, 0); } while (0)
; #define PG8_LDA(dst, b, h) do { _Pragma("unroll") for (int m = 0; m < 4; ++m) _Pragma("unroll") for (int k = 0; k < 2; ++k) dst[m][k] = *(const PG8_LAS bf16x8*)(lds + PG8_SA(b, h) + aoff + m * 2048 + k * 1024); } while (0)
; template <class Epi, class Sched, bool ALIGN_EPI = false, bool SP2 = false, bool DRAIN = true, bool XR = false>
; __device__ __forceinline__ void gemm_phase(PG8_LAS unsigned char* lds, const Gemm g, const Sched& S, const Epi& E) {
;     ...
;             const bool last = (t == nt - 2);
;             const char* a1 = cA + PG8_KOA(t) + kstep;
;             const char* a2 = last ? nA + ka0 : cA + PG8_KOA(t + 2); const char* b2 = last ? nB + kb0 : cB + PG8_KOB(t + 2);
;             const char* x2 = XR ? (last ? nX + kx0 : cX + PG8_KOX(t + 2)) : nullptr; const char* x3 = XR ? x2 + kstep : nullptr;
;             const char* a3 = a2 + kstep; const char* b3 = b2 + kstep;
;             if (last && has_next) S.a_ready(nxt);
;             if constexpr (SP2) {
;             PG8_LDB(B0, 0, 0); PG8_LDB(B1, 0, 1); PG8_SCHED; PG8_LDA(At, 0, 0); PG8_LDX(0); PG8_STAGE(PG8_SA(1, 1), a1 + hstepA, voffA);
;             PG8_WAIT_LOOP(); PG8_WAIT_L(0); PG8_BAR; PG8_MMA(0, 0, At, B0); PG8_MMA(0, 1, At, B1); PG8_MMAX(); PG8_BAR; PG8_SCHED;
;             PG8_LDA(At, 0, 1); PG8_STAGE(PG8_SB(0, 0), b2, voffB); PG8_STAGE(PG8_SB(0, 1), b2 + hstep, voffB); PG8_STAGE(PG8_SA(0, 0), a2, voffA); PG8_STAGEX(0, x2);
.LBB0_1226:
	s_barrier
	v_cndmask_b32_e64 v4, 0, 1, s[22:23]
	v_cmp_ne_u32_e64 s[8:9], 1, v4
	v_cndmask_b32_e64 v4, 0, 1, s[40:41]
	v_cmp_ne_u32_e64 s[6:7], 1, v4
	s_add_i32 s89, s50, 2
	s_and_b32 s48, s89, s82
	s_lshr_b32 s84, s48, 2
	s_lshl_b32 s36, s48, 7
	s_lshl_b64 vcc, s[84:85], 9
	s_and_b32 s36, s36, 0x100
	s_add_u32 s49, s18, vcc_lo
	s_addc_u32 s51, s19, vcc_hi
	s_add_u32 s36, s49, s36
	s_mov_b32 s49, s85
	s_addc_u32 s51, s51, 0
	s_lshl_b64 s[48:49], s[48:49], 7
	s_add_u32 vcc_lo, s14, s48
	s_addc_u32 vcc_hi, s15, s49
	s_add_u32 s58, s16, s48
	s_addc_u32 s59, s17, s49
	s_cmp_eq_u32 s37, s50
	s_cselect_b32 s49, s43, s51
	s_cselect_b32 s48, s42, s36
	s_cselect_b32 s51, s97, s59
	s_cselect_b32 s50, s90, s58
	s_cselect_b32 vcc_hi, s45, vcc_hi
	s_cselect_b32 vcc_lo, s44, vcc_lo
	s_mov_b32 m0, s65
	v_lshl_add_u64 v[224:225], vcc, 0, v[216:217]
	v_lshl_add_u64 v[226:227], vcc, 0, v[220:221]
	s_add_u32 vcc_lo, vcc_lo, s10
	ds_read_b128 v[198:201], v251 offset:16384
	ds_read_b128 v[202:205], v251 offset:17408
	ds_read_b128 v[190:193], v251 offset:18432
	ds_read_b128 v[194:197], v251 offset:19456
	ds_read_b128 v[182:185], v251 offset:20480
	ds_read_b128 v[186:189], v251 offset:21504
	ds_read_b128 v[174:177], v251 offset:22528
	ds_read_b128 v[178:181], v251 offset:23552
	global_load_lds_dwordx4 v[224:225], off
	s_mov_b32 m0, s67
	s_addc_u32 vcc_hi, vcc_hi, s11
	global_load_lds_dwordx4 v[226:227], off
	v_lshl_add_u64 v[228:229], vcc, 0, v[216:217]
	s_mov_b32 m0, s68
	v_lshl_add_u64 v[230:231], vcc, 0, v[220:221]
	global_load_lds_dwordx4 v[228:229], off
	s_mov_b32 m0, s69
	v_lshl_add_u64 v[232:233], s[48:49], 0, v[214:215]
	global_load_lds_dwordx4 v[230:231], off
	s_mov_b32 m0, s64
	v_lshl_add_u64 v[234:235], s[48:49], 0, v[218:219]
	global_load_lds_dwordx4 v[232:233], off
	s_mov_b32 m0, s70
	v_lshl_add_u64 v[4:5], s[50:51], 0, v[222:223]
	global_load_lds_dwordx4 v[234:235], off
	s_and_saveexec_b64 s[50:51], s[2:3]
	s_cbranch_execz .LBB0_1228
	s_add_i32 s36, s57, 0
	s_add_i32 m0, s36, 0x22400
	s_nop 0
	global_load_lds_dwordx4 v[4:5], off

; #define PG8_LDX(b) do { if constexpr (XR) { _Pragma("unroll") for (int k = 0; k < 2; ++k) Ax_[k] = *(const PG8_LAS bf16x8*)(lds + XR_OFF + (b) * 2048 + aoffx + k * 1024); } } while (0)
; #define PG8_MMAX() do { if constexpr (XR) { if (hasx) { __builtin_amdgcn_s_setprio(1); if (wr == 0) PG8_MMAX_(B0); else PG8_MMAX_(B1); __builtin_amdgcn_s_setprio(0); } } } while (0)
; #define PG8_WAIT_LOOP() do { if constexpr (XR) PG8_WAIT_V(9); else PG8_WAIT_V(8); } while (0)
; #define PG8_STAGE(bufoff, gbase, voff) do { _Pragma("unroll") for (int _i = 0; _i < 2; ++_i) \
;         __builtin_amdgcn_global_load_lds((const unsigned*)((const char*)(gbase) + (voff)[_i]), (PG8_LAS unsigned*)(lds + (bufoff) + ldsw + _i * 8192), 16, 0, 0); } while (0)
; #define PG8_LDA(dst, b, h) do { _Pragma("unroll") for (int m = 0; m < 4; ++m) _Pragma("unroll") for (int k = 0; k < 2; ++k) dst[m][k] = *(const PG8_LAS bf16x8*)(lds + PG8_SA(b, h) + aoff + m * 2048 + k * 1024); } while (0)
; #define PG8_LDB(dst, b, h) do { _Pragma("unroll") for (int n = 0; n < 2; ++n) _Pragma("unroll") for (int k = 0; k < 2; ++k) dst[n][k] = *(const PG8_LAS bf16x8*)(lds + PG8_SB(b, h) + boff + n * 2048 + k * 1024); } while (0)
; #define PG8_MMA(ai, bj, At, Bt) do { __builtin_amdgcn_s_setprio(1); _Pragma("unroll") for (int m = 0; m < 4; ++m) _Pragma("unroll") for (int n = 0; n < 2; ++n) _Pragma("unroll") for (int k = 0; k < 2; ++k) \
;         acc[ai][bj][m][n] = __builtin_amdgcn_mfma_f32_16x16x32_bf16(Bt[n][k], At[m][k], acc[ai][bj][m][n], 0, 0, 0); __builtin_amdgcn_s_setprio(0); } while (0)
; #define PG8_WAIT_L(n) asm volatile("s_waitcnt lgkmcnt(" #n ")" ::: "memory")
; #define PG8_BAR __builtin_amdgcn_s_barrier()
; #define PG8_SCHED __builtin_amdgcn_sched_barrier(0)
; template <class Epi, class Sched, bool ALIGN_EPI = false, bool SP2 = false, bool DRAIN = true, bool XR = false>
; __device__ __forceinline__ void gemm_phase(PG8_LAS unsigned char* lds, const Gemm g, const Sched& S, const Epi& E) {
;     ...
;             PG8_LDB(B0, 0, 0); PG8_LDB(B1, 0, 1); PG8_SCHED; PG8_LDA(At, 0, 0); PG8_LDX(0); PG8_STAGE(PG8_SA(1, 1), a1 + hstepA, voffA);
;             PG8_WAIT_LOOP(); PG8_WAIT_L(0); PG8_BAR; PG8_MMA(0, 0, At, B0); PG8_MMA(0, 1, At, B1); PG8_MMAX(); PG8_BAR; PG8_SCHED;
.LBB0_1359:
	v_add_u32_e32 v2, 0x10000, v248
	s_add_i32 s4, s90, -2
	ds_read_b128 v[158:161], v2
	ds_read_b128 v[162:165], v2 offset:1024
	ds_read_b128 v[166:169], v2 offset:2048
	ds_read_b128 v[170:173], v2 offset:3072
	v_add_u32_e32 v2, 0x14000, v248
	s_and_b32 s6, s4, s73
	ds_read_b128 v[142:145], v2
	ds_read_b128 v[146:149], v2 offset:1024
	ds_read_b128 v[150:153], v2 offset:2048
	ds_read_b128 v[154:157], v2 offset:3072
	s_lshr_b32 s84, s6, 2
	s_lshl_b32 s6, s6, 7
	s_lshl_b64 s[4:5], s[84:85], 9
	s_and_b32 s6, s6, 0x100
	s_add_u32 s4, s56, s4
	s_addc_u32 s5, s57, s5
	s_add_u32 s4, s4, s6
	s_addc_u32 s5, s5, 0
	s_add_u32 s4, s4, s28
	s_addc_u32 s5, s5, s29
	v_lshl_add_u64 v[4:5], s[4:5], 0, v[220:221]
	v_add_u32_e32 v2, 0x22400, v250
	v_lshl_add_u64 v[4:5], v[4:5], 0, s[86:87]
	s_add_i32 m0, s13, 0xc000
	ds_read_b128 v[182:185], v249
	ds_read_b128 v[186:189], v249 offset:1024
	ds_read_b128 v[190:193], v249 offset:2048
	ds_read_b128 v[194:197], v249 offset:3072
	ds_read_b128 v[198:201], v249 offset:4096
	ds_read_b128 v[202:205], v249 offset:5120
	ds_read_b128 v[206:209], v249 offset:6144
	ds_read_b128 v[224:227], v249 offset:7168
	ds_read_b128 v[174:177], v2
	ds_read_b128 v[178:181], v2 offset:1024
	global_load_lds_dwordx4 v[4:5], off
	v_lshl_add_u64 v[4:5], s[4:5], 0, v[216:217]
	v_lshl_add_u64 v[4:5], v[4:5], 0, s[86:87]
	s_add_i32 m0, s13, 0xe000
	s_nop 0
	global_load_lds_dwordx4 v[4:5], off
	s_waitcnt vmcnt(9)
	s_waitcnt lgkmcnt(0)
	s_setprio 1
	s_barrier
	v_mfma_f32_16x16x32_bf16 v[138:141], v[158:161], v[182:185], v[138:141]
	v_mfma_f32_16x16x32_bf16 v[134:137], v[166:169], v[182:185], v[134:137]
	v_mfma_f32_16x16x32_bf16 v[122:125], v[158:161], v[190:193], v[122:125]
	v_mfma_f32_16x16x32_bf16 v[118:121], v[166:169], v[190:193], v[118:121]
	v_mfma_f32_16x16x32_bf16 v[106:109], v[158:161], v[198:201], v[106:109]
	v_mfma_f32_16x16x32_bf16 v[102:105], v[166:169], v[198:201], v[102:105]
	v_mfma_f32_16x16x32_bf16 v[90:93], v[158:161], v[206:209], v[90:93]
	v_mfma_f32_16x16x32_bf16 v[86:89], v[166:169], v[206:209], v[86:89]
	v_mfma_f32_16x16x32_bf16 v[138:141], v[162:165], v[186:189], v[138:141]
	v_mfma_f32_16x16x32_bf16 v[134:137], v[170:173], v[186:189], v[134:137]
	v_mfma_f32_16x16x32_bf16 v[122:125], v[162:165], v[194:197], v[122:125]
	v_mfma_f32_16x16x32_bf16 v[118:121], v[170:173], v[194:197], v[118:121]
	v_mfma_f32_16x16x32_bf16 v[106:109], v[162:165], v[202:205], v[106:109]
	v_mfma_f32_16x16x32_bf16 v[102:105], v[170:173], v[202:205], v[102:105]
	v_mfma_f32_16x16x32_bf16 v[90:93], v[162:165], v[224:227], v[90:93]
	v_mfma_f32_16x16x32_bf16 v[86:89], v[170:173], v[224:227], v[86:89]
	v_mfma_f32_16x16x32_bf16 v[130:133], v[142:145], v[182:185], v[130:133]
	v_mfma_f32_16x16x32_bf16 v[126:129], v[150:153], v[182:185], v[126:129]
	v_mfma_f32_16x16x32_bf16 v[114:117], v[142:145], v[190:193], v[114:117]
	v_mfma_f32_16x16x32_bf16 v[110:113], v[150:153], v[190:193], v[110:113]
	v_mfma_f32_16x16x32_bf16 v[98:101], v[142:145], v[198:201], v[98:101]
	v_mfma_f32_16x16x32_bf16 v[94:97], v[150:153], v[198:201], v[94:97]
	v_mfma_f32_16x16x32_bf16 v[82:85], v[142:145], v[206:209], v[82:85]
	v_mfma_f32_16x16x32_bf16 v[78:81], v[150:153], v[206:209], v[78:81]
	v_mfma_f32_16x16x32_bf16 v[130:133], v[146:149], v[186:189], v[130:133]
	v_mfma_f32_16x16x32_bf16 v[126:129], v[154:157], v[186:189], v[126:129]
	v_mfma_f32_16x16x32_bf16 v[114:117], v[146:149], v[194:197], v[114:117]
	v_mfma_f32_16x16x32_bf16 v[110:113], v[154:157], v[194:197], v[110:113]
	v_mfma_f32_16x16x32_bf16 v[98:101], v[146:149], v[202:205], v[98:101]
	v_mfma_f32_16x16x32_bf16 v[94:97], v[154:157], v[202:205], v[94:97]
	v_mfma_f32_16x16x32_bf16 v[82:85], v[146:149], v[224:227], v[82:85]
	v_mfma_f32_16x16x32_bf16 v[78:81], v[154:157], v[224:227], v[78:81]
	s_setprio 0
	s_cmp_eq_u64 s[46:47], 0
	s_cbranch_scc1 .LBB0_1365
	s_setprio 1
	s_mov_b64 s[60:61], -1
	s_cmp_eq_u64 s[44:45], 0
	s_cbranch_scc1 .LBB0_1362
	v_mfma_f32_16x16x32_bf16 v[10:13], v[142:145], v[174:177], v[10:13]
	s_mov_b64 s[60:61], 0
	v_mfma_f32_16x16x32_bf16 v[6:9], v[150:153], v[174:177], v[6:9]
	v_mfma_f32_16x16x32_bf16 v[10:13], v[146:149], v[178:181], v[10:13]
	v_mfma_f32_16x16x32_bf16 v[6:9], v[154:157], v[178:181], v[6:9]

; #define PG8_STAGEX(b, gbase) do { if constexpr (XR) { if (lane < 16) __builtin_amdgcn_global_load_lds((const unsigned*)((const char*)(gbase) + voffX), (PG8_LAS unsigned*)(lds + XR_OFF + (b) * 2048 + wid * 256), 16, 0, 0); } } while (0)
; #define PG8_LDX(b) do { if constexpr (XR) { _Pragma("unroll") for (int k = 0; k < 2; ++k) Ax_[k] = *(const PG8_LAS bf16x8*)(lds + XR_OFF + (b) * 2048 + aoffx + k * 1024); } } while (0)
; #define PG8_MMAX() do { if constexpr (XR) { if (hasx) { __builtin_amdgcn_s_setprio(1); if (wr == 0) PG8_MMAX_(B0); else PG8_MMAX_(B1); __builtin_amdgcn_s_setprio(0); } } } while (0)
; #define PG8_WAIT_LOOP() do { if constexpr (XR) PG8_WAIT_V(9); else PG8_WAIT_V(8); } while (0)
; #define PG8_STAGE(bufoff, gbase, voff) do { _Pragma("unroll") for (int _i = 0; _i < 2; ++_i) \
;         __builtin_amdgcn_global_load_lds((const unsigned*)((const char*)(gbase) + (voff)[_i]), (PG8_LAS unsigned*)(lds + (bufoff) + ldsw + _i * 8192), 16, 0, 0); } while (0)
; #define PG8_LDA(dst, b, h) do { _Pragma("unroll") for (int m = 0; m < 4; ++m) _Pragma("unroll") for (int k = 0; k < 2; ++k) dst[m][k] = *(const PG8_LAS bf16x8*)(lds + PG8_SA(b, h) + aoff + m * 2048 + k * 1024); } while (0)
; template <class Epi, class Sched, bool ALIGN_EPI = false, bool SP2 = false, bool DRAIN = true, bool XR = false>
; __device__ __forceinline__ void gemm_phase(PG8_LAS unsigned char* lds, const Gemm g, const Sched& S, const Epi& E) {
;     ...
;             const bool last = (t == nt - 2);
;             const char* a1 = cA + PG8_KOA(t) + kstep;
;             const char* a2 = last ? nA + ka0 : cA + PG8_KOA(t + 2); const char* b2 = last ? nB + kb0 : cB + PG8_KOB(t + 2);
;             const char* x2 = XR ? (last ? nX + kx0 : cX + PG8_KOX(t + 2)) : nullptr; const char* x3 = XR ? x2 + kstep : nullptr;
;             const char* a3 = a2 + kstep; const char* b3 = b2 + kstep;
;             if (last && has_next) S.a_ready(nxt);
;             if constexpr (SP2) {
;             PG8_LDB(B0, 0, 0); PG8_LDB(B1, 0, 1); PG8_SCHED; PG8_LDA(At, 0, 0); PG8_LDX(0); PG8_STAGE(PG8_SA(1, 1), a1 + hstepA, voffA);
;             PG8_WAIT_LOOP(); PG8_WAIT_L(0); PG8_BAR; PG8_MMA(0, 0, At, B0); PG8_MMA(0, 1, At, B1); PG8_MMAX(); PG8_BAR; PG8_SCHED;
;             PG8_LDA(At, 0, 1); PG8_STAGE(PG8_SB(0, 0), b2, voffB); PG8_STAGE(PG8_SB(0, 1), b2 + hstep, voffB); PG8_STAGE(PG8_SA(0, 0), a2, voffA); PG8_STAGEX(0, x2);
.LBB0_1365:
	s_barrier
	v_cndmask_b32_e64 v2, 0, 1, s[46:47]
	v_cmp_ne_u32_e64 s[6:7], 1, v2
	v_cndmask_b32_e64 v2, 0, 1, s[44:45]
	v_cmp_ne_u32_e64 s[4:5], 1, v2
	s_and_b32 s8, s90, s73
	s_lshr_b32 s84, s8, 2
	s_lshl_b32 s9, s8, 7
	s_lshl_b64 s[20:21], s[84:85], 9
	s_and_b32 s9, s9, 0x100
	s_add_u32 s20, s56, s20
	s_addc_u32 s21, s57, s21
	s_add_u32 s20, s20, s9
	s_mov_b32 s9, s85
	s_addc_u32 s21, s21, 0
	s_lshl_b64 s[8:9], s[8:9], 7
	s_add_u32 s36, s54, s8
	s_addc_u32 s62, s55, s9
	s_add_u32 s8, s58, s8
	s_addc_u32 s9, s59, s9
	s_cmp_eq_u32 s65, s90
	s_cselect_b32 s61, s49, s21
	s_cselect_b32 s60, s48, s20
	s_cselect_b32 s9, s88, s9
	s_cselect_b32 s8, s89, s8
	s_cselect_b32 s21, s51, s62
	s_cselect_b32 s20, s50, s36
	s_mov_b32 m0, s14
	v_lshl_add_u64 v[224:225], s[20:21], 0, v[218:219]
	v_lshl_add_u64 v[226:227], s[20:21], 0, v[214:215]
	s_add_u32 s20, s20, s28
	ds_read_b128 v[198:201], v249 offset:16384
	ds_read_b128 v[202:205], v249 offset:17408
	ds_read_b128 v[190:193], v249 offset:18432
	ds_read_b128 v[194:197], v249 offset:19456
	ds_read_b128 v[182:185], v249 offset:20480
	ds_read_b128 v[186:189], v249 offset:21504
	ds_read_b128 v[174:177], v249 offset:22528
	ds_read_b128 v[178:181], v249 offset:23552
	global_load_lds_dwordx4 v[224:225], off
	s_mov_b32 m0, s15
	s_addc_u32 s21, s21, s29
	global_load_lds_dwordx4 v[226:227], off
	v_lshl_add_u64 v[228:229], s[20:21], 0, v[218:219]
	s_mov_b32 m0, s16
	v_lshl_add_u64 v[230:231], s[20:21], 0, v[214:215]
	global_load_lds_dwordx4 v[228:229], off
	s_mov_b32 m0, s17
	v_lshl_add_u64 v[232:233], s[60:61], 0, v[220:221]
	global_load_lds_dwordx4 v[230:231], off
	s_mov_b32 m0, s13
	v_lshl_add_u64 v[234:235], s[60:61], 0, v[216:217]
	global_load_lds_dwordx4 v[232:233], off
	s_mov_b32 m0, s18
	v_lshl_add_u64 v[4:5], s[8:9], 0, v[222:223]
	global_load_lds_dwordx4 v[234:235], off
	s_and_saveexec_b64 s[62:63], s[0:1]
	s_cbranch_execz .LBB0_1367
	s_add_i32 s8, s12, 0
	s_add_i32 m0, s8, 0x22400
	s_nop 0
	global_load_lds_dwordx4 v[4:5], off

; #define PG8_LDX(b) do { if constexpr (XR) { _Pragma("unroll") for (int k = 0; k < 2; ++k) Ax_[k] = *(const PG8_LAS bf16x8*)(lds + XR_OFF + (b) * 2048 + aoffx + k * 1024); } } while (0)
; #define PG8_MMAX() do { if constexpr (XR) { if (hasx) { __builtin_amdgcn_s_setprio(1); if (wr == 0) PG8_MMAX_(B0); else PG8_MMAX_(B1); __builtin_amdgcn_s_setprio(0); } } } while (0)
; #define PG8_WAIT_LOOP() do { if constexpr (XR) PG8_WAIT_V(9); else PG8_WAIT_V(8); } while (0)
; #define PG8_STAGE(bufoff, gbase, voff) do { _Pragma("unroll") for (int _i = 0; _i < 2; ++_i) \
;         __builtin_amdgcn_global_load_lds((const unsigned*)((const char*)(gbase) + (voff)[_i]), (PG8_LAS unsigned*)(lds + (bufoff) + ldsw + _i * 8192), 16, 0, 0); } while (0)
; #define PG8_LDA(dst, b, h) do { _Pragma("unroll") for (int m = 0; m < 4; ++m) _Pragma("unroll") for (int k = 0; k < 2; ++k) dst[m][k] = *(const PG8_LAS bf16x8*)(lds + PG8_SA(b, h) + aoff + m * 2048 + k * 1024); } while (0)
; #define PG8_LDB(dst, b, h) do { _Pragma("unroll") for (int n = 0; n < 2; ++n) _Pragma("unroll") for (int k = 0; k < 2; ++k) dst[n][k] = *(const PG8_LAS bf16x8*)(lds + PG8_SB(b, h) + boff + n * 2048 + k * 1024); } while (0)
; #define PG8_MMA(ai, bj, At, Bt) do { __builtin_amdgcn_s_setprio(1); _Pragma("unroll") for (int m = 0; m < 4; ++m) _Pragma("unroll") for (int n = 0; n < 2; ++n) _Pragma("unroll") for (int k = 0; k < 2; ++k) \
;         acc[ai][bj][m][n] = __builtin_amdgcn_mfma_f32_16x16x32_bf16(Bt[n][k], At[m][k], acc[ai][bj][m][n], 0, 0, 0); __builtin_amdgcn_s_setprio(0); } while (0)
; #define PG8_WAIT_L(n) asm volatile("s_waitcnt lgkmcnt(" #n ")" ::: "memory")
; #define PG8_BAR __builtin_amdgcn_s_barrier()
; #define PG8_SCHED __builtin_amdgcn_sched_barrier(0)
; template <class Epi, class Sched, bool ALIGN_EPI = false, bool SP2 = false, bool DRAIN = true, bool XR = false>
; __device__ __forceinline__ void gemm_phase(PG8_LAS unsigned char* lds, const Gemm g, const Sched& S, const Epi& E) {
;     ...
;             PG8_LDB(B0, 0, 0); PG8_LDB(B1, 0, 1); PG8_SCHED; PG8_LDA(At, 0, 0); PG8_LDX(0); PG8_STAGE(PG8_SA(1, 1), a1 + hstepA, voffA);
;             PG8_WAIT_LOOP(); PG8_WAIT_L(0); PG8_BAR; PG8_MMA(0, 0, At, B0); PG8_MMA(0, 1, At, B1); PG8_MMAX(); PG8_BAR; PG8_SCHED;
.LBB0_1501:
	s_add_i32 s64, s83, s70
	v_add_u32_e32 v140, 0x10000, v248
	v_add_u32_e32 v152, 0x14000, v248
	s_and_b32 s6, s64, s97
	ds_read_b128 v[156:159], v140
	ds_read_b128 v[160:163], v140 offset:1024
	ds_read_b128 v[164:167], v140 offset:2048
	ds_read_b128 v[168:171], v140 offset:3072
	ds_read_b128 v[140:143], v152
	ds_read_b128 v[144:147], v152 offset:1024
	ds_read_b128 v[148:151], v152 offset:2048
	ds_read_b128 v[152:155], v152 offset:3072
	s_lshr_b32 s84, s6, 2
	s_lshl_b32 s6, s6, 7
	s_lshl_b64 s[4:5], s[84:85], 9
	s_and_b32 s6, s6, 0x100
	s_add_u32 s4, s40, s4
	s_addc_u32 s5, s41, s5
	s_add_u32 s4, s4, s6
	s_addc_u32 s5, s5, 0
	s_add_u32 s4, s4, s28
	s_addc_u32 s5, s5, s29
	v_lshl_add_u64 v[212:213], s[4:5], 0, v[204:205]
	v_add_u32_e32 v176, 0x22400, v250
	v_lshl_add_u64 v[212:213], v[212:213], 0, s[86:87]
	s_add_i32 m0, s90, 0xc000
	ds_read_b128 v[180:183], v249
	ds_read_b128 v[184:187], v249 offset:1024
	ds_read_b128 v[188:191], v249 offset:2048
	ds_read_b128 v[192:195], v249 offset:3072
	ds_read_b128 v[196:199], v249 offset:4096
	ds_read_b128 v[200:203], v249 offset:5120
	ds_read_b128 v[206:209], v249 offset:6144
	ds_read_b128 v[222:225], v249 offset:7168
	ds_read_b128 v[172:175], v176
	ds_read_b128 v[176:179], v176 offset:1024
	global_load_lds_dwordx4 v[212:213], off
	v_lshl_add_u64 v[212:213], s[4:5], 0, v[216:217]
	v_lshl_add_u64 v[212:213], v[212:213], 0, s[86:87]
	s_add_i32 m0, s90, 0xe000
	s_nop 0
	global_load_lds_dwordx4 v[212:213], off
	s_waitcnt vmcnt(9)
	s_waitcnt lgkmcnt(0)
	s_setprio 1
	s_barrier
	v_mfma_f32_16x16x32_bf16 v[136:139], v[156:159], v[180:183], v[136:139]
	v_mfma_f32_16x16x32_bf16 v[132:135], v[164:167], v[180:183], v[132:135]
	v_mfma_f32_16x16x32_bf16 v[128:131], v[156:159], v[188:191], v[128:131]
	v_mfma_f32_16x16x32_bf16 v[124:127], v[164:167], v[188:191], v[124:127]
	v_mfma_f32_16x16x32_bf16 v[120:123], v[156:159], v[196:199], v[120:123]
	v_mfma_f32_16x16x32_bf16 v[116:119], v[164:167], v[196:199], v[116:119]
	v_mfma_f32_16x16x32_bf16 v[112:115], v[156:159], v[206:209], v[112:115]
	v_mfma_f32_16x16x32_bf16 v[108:111], v[164:167], v[206:209], v[108:111]
	v_mfma_f32_16x16x32_bf16 v[136:139], v[160:163], v[184:187], v[136:139]
	v_mfma_f32_16x16x32_bf16 v[132:135], v[168:171], v[184:187], v[132:135]
	v_mfma_f32_16x16x32_bf16 v[128:131], v[160:163], v[192:195], v[128:131]
	v_mfma_f32_16x16x32_bf16 v[124:127], v[168:171], v[192:195], v[124:127]
	v_mfma_f32_16x16x32_bf16 v[120:123], v[160:163], v[200:203], v[120:123]
	v_mfma_f32_16x16x32_bf16 v[116:119], v[168:171], v[200:203], v[116:119]
	v_mfma_f32_16x16x32_bf16 v[112:115], v[160:163], v[222:225], v[112:115]
	v_mfma_f32_16x16x32_bf16 v[108:111], v[168:171], v[222:225], v[108:111]
	v_mfma_f32_16x16x32_bf16 v[104:107], v[140:143], v[180:183], v[104:107]
	v_mfma_f32_16x16x32_bf16 v[100:103], v[148:151], v[180:183], v[100:103]
	v_mfma_f32_16x16x32_bf16 v[96:99], v[140:143], v[188:191], v[96:99]
	v_mfma_f32_16x16x32_bf16 v[92:95], v[148:151], v[188:191], v[92:95]
	v_mfma_f32_16x16x32_bf16 v[88:91], v[140:143], v[196:199], v[88:91]
	v_mfma_f32_16x16x32_bf16 v[84:87], v[148:151], v[196:199], v[84:87]
	v_mfma_f32_16x16x32_bf16 v[80:83], v[140:143], v[206:209], v[80:83]
	v_mfma_f32_16x16x32_bf16 v[76:79], v[148:151], v[206:209], v[76:79]
	v_mfma_f32_16x16x32_bf16 v[104:107], v[144:147], v[184:187], v[104:107]
	v_mfma_f32_16x16x32_bf16 v[100:103], v[152:155], v[184:187], v[100:103]
	v_mfma_f32_16x16x32_bf16 v[96:99], v[144:147], v[192:195], v[96:99]
	v_mfma_f32_16x16x32_bf16 v[92:95], v[152:155], v[192:195], v[92:95]
	v_mfma_f32_16x16x32_bf16 v[88:91], v[144:147], v[200:203], v[88:91]
	v_mfma_f32_16x16x32_bf16 v[84:87], v[152:155], v[200:203], v[84:87]
	v_mfma_f32_16x16x32_bf16 v[80:83], v[144:147], v[222:225], v[80:83]
	v_mfma_f32_16x16x32_bf16 v[76:79], v[152:155], v[222:225], v[76:79]
	s_setprio 0
	s_cmp_eq_u64 s[46:47], 0
	s_cbranch_scc1 .LBB0_1507
	s_setprio 1
	s_mov_b64 s[62:63], -1
	s_cmp_eq_u64 s[52:53], 0
	s_cbranch_scc1 .LBB0_1504
	v_mfma_f32_16x16x32_bf16 v[8:11], v[140:143], v[172:175], v[8:11]
	s_mov_b64 s[62:63], 0
	v_mfma_f32_16x16x32_bf16 v[4:7], v[148:151], v[172:175], v[4:7]
	v_mfma_f32_16x16x32_bf16 v[8:11], v[144:147], v[176:179], v[8:11]
	v_mfma_f32_16x16x32_bf16 v[4:7], v[152:155], v[176:179], v[4:7]

; #define PG8_STAGEX(b, gbase) do { if constexpr (XR) { if (lane < 16) __builtin_amdgcn_global_load_lds((const unsigned*)((const char*)(gbase) + voffX), (PG8_LAS unsigned*)(lds + XR_OFF + (b) * 2048 + wid * 256), 16, 0, 0); } } while (0)
; #define PG8_LDX(b) do { if constexpr (XR) { _Pragma("unroll") for (int k = 0; k < 2; ++k) Ax_[k] = *(const PG8_LAS bf16x8*)(lds + XR_OFF + (b) * 2048 + aoffx + k * 1024); } } while (0)
; #define PG8_MMAX() do { if constexpr (XR) { if (hasx) { __builtin_amdgcn_s_setprio(1); if (wr == 0) PG8_MMAX_(B0); else PG8_MMAX_(B1); __builtin_amdgcn_s_setprio(0); } } } while (0)
; #define PG8_WAIT_LOOP() do { if constexpr (XR) PG8_WAIT_V(9); else PG8_WAIT_V(8); } while (0)
; #define PG8_STAGE(bufoff, gbase, voff) do { _Pragma("unroll") for (int _i = 0; _i < 2; ++_i) \
;         __builtin_amdgcn_global_load_lds((const unsigned*)((const char*)(gbase) + (voff)[_i]), (PG8_LAS unsigned*)(lds + (bufoff) + ldsw + _i * 8192), 16, 0, 0); } while (0)
; #define PG8_LDA(dst, b, h) do { _Pragma("unroll") for (int m = 0; m < 4; ++m) _Pragma("unroll") for (int k = 0; k < 2; ++k) dst[m][k] = *(const PG8_LAS bf16x8*)(lds + PG8_SA(b, h) + aoff + m * 2048 + k * 1024); } while (0)
; template <class Epi, class Sched, bool ALIGN_EPI = false, bool SP2 = false, bool DRAIN = true, bool XR = false>
; __device__ __forceinline__ void gemm_phase(PG8_LAS unsigned char* lds, const Gemm g, const Sched& S, const Epi& E) {
;     ...
;             const bool last = (t == nt - 2);
;             const char* a1 = cA + PG8_KOA(t) + kstep;
;             const char* a2 = last ? nA + ka0 : cA + PG8_KOA(t + 2); const char* b2 = last ? nB + kb0 : cB + PG8_KOB(t + 2);
;             const char* x2 = XR ? (last ? nX + kx0 : cX + PG8_KOX(t + 2)) : nullptr; const char* x3 = XR ? x2 + kstep : nullptr;
;             const char* a3 = a2 + kstep; const char* b3 = b2 + kstep;
;             if (last && has_next) S.a_ready(nxt);
;             if constexpr (SP2) {
;             PG8_LDB(B0, 0, 0); PG8_LDB(B1, 0, 1); PG8_SCHED; PG8_LDA(At, 0, 0); PG8_LDX(0); PG8_STAGE(PG8_SA(1, 1), a1 + hstepA, voffA);
;             PG8_WAIT_LOOP(); PG8_WAIT_L(0); PG8_BAR; PG8_MMA(0, 0, At, B0); PG8_MMA(0, 1, At, B1); PG8_MMAX(); PG8_BAR; PG8_SCHED;
;             PG8_LDA(At, 0, 1); PG8_STAGE(PG8_SB(0, 0), b2, voffB); PG8_STAGE(PG8_SB(0, 1), b2 + hstep, voffB); PG8_STAGE(PG8_SA(0, 0), a2, voffA); PG8_STAGEX(0, x2);
.LBB0_1507:
	s_barrier
	v_cndmask_b32_e64 v180, 0, 1, s[46:47]
	v_cmp_ne_u32_e64 s[6:7], 1, v180
	v_cndmask_b32_e64 v180, 0, 1, s[52:53]
	v_cmp_ne_u32_e64 s[4:5], 1, v180
	s_add_i32 s64, s64, 2
	s_and_b32 s62, s64, s97
	s_lshr_b32 s84, s62, 2
	s_lshl_b32 s36, s62, 7
	s_lshl_b64 s[64:65], s[84:85], 9
	s_and_b32 s36, s36, 0x100
	s_add_u32 s63, s40, s64
	s_addc_u32 s64, s41, s65
	s_add_u32 s36, s63, s36
	s_mov_b32 s63, s85
	s_addc_u32 s64, s64, 0
	s_lshl_b64 s[62:63], s[62:63], 7
	s_add_u32 vcc_lo, s34, s62
	s_addc_u32 vcc_hi, s35, s63
	s_add_u32 s81, s42, s62
	s_addc_u32 s65, s43, s63
	s_cmp_eq_u32 s91, s70
	s_cselect_b32 s63, s8, s64
	s_cselect_b32 s62, s78, s36
	s_cselect_b32 s65, s69, s65
	s_cselect_b32 s64, s21, s81
	s_cselect_b32 vcc_hi, s20, vcc_hi
	s_cselect_b32 vcc_lo, s9, vcc_lo
	s_mov_b32 m0, s16
	v_lshl_add_u64 v[224:225], vcc, 0, v[214:215]
	v_lshl_add_u64 v[226:227], vcc, 0, v[218:219]
	s_add_u32 vcc_lo, vcc_lo, s28
	ds_read_b128 v[196:199], v249 offset:16384
	ds_read_b128 v[200:203], v249 offset:17408
	ds_read_b128 v[188:191], v249 offset:18432
	ds_read_b128 v[192:195], v249 offset:19456
	ds_read_b128 v[180:183], v249 offset:20480
	ds_read_b128 v[184:187], v249 offset:21504
	ds_read_b128 v[172:175], v249 offset:22528
	ds_read_b128 v[176:179], v249 offset:23552
	global_load_lds_dwordx4 v[224:225], off
	s_mov_b32 m0, s17
	s_addc_u32 vcc_hi, vcc_hi, s29
	global_load_lds_dwordx4 v[226:227], off
	v_lshl_add_u64 v[228:229], vcc, 0, v[214:215]
	s_mov_b32 m0, s93
	v_lshl_add_u64 v[230:231], vcc, 0, v[218:219]
	global_load_lds_dwordx4 v[228:229], off
	s_mov_b32 m0, s24
	v_lshl_add_u64 v[232:233], s[62:63], 0, v[204:205]
	global_load_lds_dwordx4 v[230:231], off
	s_mov_b32 m0, s90
	v_lshl_add_u64 v[234:235], s[62:63], 0, v[216:217]
	global_load_lds_dwordx4 v[232:233], off
	s_mov_b32 m0, s25
	v_lshl_add_u64 v[222:223], s[64:65], 0, v[220:221]
	global_load_lds_dwordx4 v[234:235], off
	s_and_saveexec_b64 s[64:65], s[2:3]
	s_cbranch_execz .LBB0_1509
	s_add_i32 s36, s26, 0
	s_add_i32 m0, s36, 0x22400
	s_nop 0
	global_load_lds_dwordx4 v[222:223], off

; #define PG8_LDX(b) do { if constexpr (XR) { _Pragma("unroll") for (int k = 0; k < 2; ++k) Ax_[k] = *(const PG8_LAS bf16x8*)(lds + XR_OFF + (b) * 2048 + aoffx + k * 1024); } } while (0)
; #define PG8_MMAX() do { if constexpr (XR) { if (hasx) { __builtin_amdgcn_s_setprio(1); if (wr == 0) PG8_MMAX_(B0); else PG8_MMAX_(B1); __builtin_amdgcn_s_setprio(0); } } } while (0)
; #define PG8_WAIT_LOOP() do { if constexpr (XR) PG8_WAIT_V(9); else PG8_WAIT_V(8); } while (0)
; #define PG8_STAGE(bufoff, gbase, voff) do { _Pragma("unroll") for (int _i = 0; _i < 2; ++_i) \
;         __builtin_amdgcn_global_load_lds((const unsigned*)((const char*)(gbase) + (voff)[_i]), (PG8_LAS unsigned*)(lds + (bufoff) + ldsw + _i * 8192), 16, 0, 0); } while (0)
; #define PG8_LDA(dst, b, h) do { _Pragma("unroll") for (int m = 0; m < 4; ++m) _Pragma("unroll") for (int k = 0; k < 2; ++k) dst[m][k] = *(const PG8_LAS bf16x8*)(lds + PG8_SA(b, h) + aoff + m * 2048 + k * 1024); } while (0)
; #define PG8_LDB(dst, b, h) do { _Pragma("unroll") for (int n = 0; n < 2; ++n) _Pragma("unroll") for (int k = 0; k < 2; ++k) dst[n][k] = *(const PG8_LAS bf16x8*)(lds + PG8_SB(b, h) + boff + n * 2048 + k * 1024); } while (0)
; #define PG8_MMA(ai, bj, At, Bt) do { __builtin_amdgcn_s_setprio(1); _Pragma("unroll") for (int m = 0; m < 4; ++m) _Pragma("unroll") for (int n = 0; n < 2; ++n) _Pragma("unroll") for (int k = 0; k < 2; ++k) \
;         acc[ai][bj][m][n] = __builtin_amdgcn_mfma_f32_16x16x32_bf16(Bt[n][k], At[m][k], acc[ai][bj][m][n], 0, 0, 0); __builtin_amdgcn_s_setprio(0); } while (0)
; #define PG8_WAIT_L(n) asm volatile("s_waitcnt lgkmcnt(" #n ")" ::: "memory")
; #define PG8_BAR __builtin_amdgcn_s_barrier()
; #define PG8_SCHED __builtin_amdgcn_sched_barrier(0)
; template <class Epi, class Sched, bool ALIGN_EPI = false, bool SP2 = false, bool DRAIN = true, bool XR = false>
; __device__ __forceinline__ void gemm_phase(PG8_LAS unsigned char* lds, const Gemm g, const Sched& S, const Epi& E) {
;     ...
;             PG8_LDB(B0, 0, 0); PG8_LDB(B1, 0, 1); PG8_SCHED; PG8_LDA(At, 0, 0); PG8_LDX(0); PG8_STAGE(PG8_SA(1, 1), a1 + hstepA, voffA);
;             PG8_WAIT_LOOP(); PG8_WAIT_L(0); PG8_BAR; PG8_MMA(0, 0, At, B0); PG8_MMA(0, 1, At, B1); PG8_MMAX(); PG8_BAR; PG8_SCHED;
.LBB0_1652:
	v_add_u32_e32 v2, 0x10000, v248
	s_add_i32 s46, s54, s89
	ds_read_b128 v[158:161], v2
	ds_read_b128 v[162:165], v2 offset:1024
	ds_read_b128 v[166:169], v2 offset:2048
	ds_read_b128 v[170:173], v2 offset:3072
	v_add_u32_e32 v2, 0x14000, v248
	s_and_b32 s6, s46, s59
	ds_read_b128 v[142:145], v2
	ds_read_b128 v[146:149], v2 offset:1024
	ds_read_b128 v[150:153], v2 offset:2048
	ds_read_b128 v[154:157], v2 offset:3072
	s_lshr_b32 s84, s6, 2
	s_lshl_b32 s6, s6, 7
	s_lshl_b64 s[0:1], s[84:85], 17
	s_and_b32 s6, s6, 0x100
	s_add_u32 s0, s40, s0
	s_addc_u32 s1, s41, s1
	s_add_u32 s0, s0, s6
	s_addc_u32 s1, s1, 0
	s_add_u32 s0, s0, 0x10080
	s_addc_u32 s1, s1, 0
	v_add_u32_e32 v2, 0x22400, v250
	v_lshl_add_u64 v[4:5], s[0:1], 0, v[214:215]
	s_add_i32 m0, s63, 0xc000
	ds_read_b128 v[182:185], v249
	ds_read_b128 v[186:189], v249 offset:1024
	ds_read_b128 v[190:193], v249 offset:2048
	ds_read_b128 v[194:197], v249 offset:3072
	ds_read_b128 v[198:201], v249 offset:4096
	ds_read_b128 v[202:205], v249 offset:5120
	ds_read_b128 v[206:209], v249 offset:6144
	ds_read_b128 v[224:227], v249 offset:7168
	ds_read_b128 v[174:177], v2
	ds_read_b128 v[178:181], v2 offset:1024
	global_load_lds_dwordx4 v[4:5], off
	v_lshl_add_u64 v[4:5], s[0:1], 0, v[218:219]
	s_add_i32 m0, s63, 0xe000
	s_nop 0
	global_load_lds_dwordx4 v[4:5], off
	s_waitcnt vmcnt(9)
	s_waitcnt lgkmcnt(0)
	s_setprio 1
	s_barrier
	v_mfma_f32_16x16x32_bf16 v[138:141], v[158:161], v[182:185], v[138:141]
	v_mfma_f32_16x16x32_bf16 v[134:137], v[166:169], v[182:185], v[134:137]
	v_mfma_f32_16x16x32_bf16 v[122:125], v[158:161], v[190:193], v[122:125]
	v_mfma_f32_16x16x32_bf16 v[118:121], v[166:169], v[190:193], v[118:121]
	v_mfma_f32_16x16x32_bf16 v[106:109], v[158:161], v[198:201], v[106:109]
	v_mfma_f32_16x16x32_bf16 v[102:105], v[166:169], v[198:201], v[102:105]
	v_mfma_f32_16x16x32_bf16 v[90:93], v[158:161], v[206:209], v[90:93]
	v_mfma_f32_16x16x32_bf16 v[86:89], v[166:169], v[206:209], v[86:89]
	v_mfma_f32_16x16x32_bf16 v[138:141], v[162:165], v[186:189], v[138:141]
	v_mfma_f32_16x16x32_bf16 v[134:137], v[170:173], v[186:189], v[134:137]
	v_mfma_f32_16x16x32_bf16 v[122:125], v[162:165], v[194:197], v[122:125]
	v_mfma_f32_16x16x32_bf16 v[118:121], v[170:173], v[194:197], v[118:121]
	v_mfma_f32_16x16x32_bf16 v[106:109], v[162:165], v[202:205], v[106:109]
	v_mfma_f32_16x16x32_bf16 v[102:105], v[170:173], v[202:205], v[102:105]
	v_mfma_f32_16x16x32_bf16 v[90:93], v[162:165], v[224:227], v[90:93]
	v_mfma_f32_16x16x32_bf16 v[86:89], v[170:173], v[224:227], v[86:89]
	v_mfma_f32_16x16x32_bf16 v[130:133], v[142:145], v[182:185], v[130:133]
	v_mfma_f32_16x16x32_bf16 v[126:129], v[150:153], v[182:185], v[126:129]
	v_mfma_f32_16x16x32_bf16 v[114:117], v[142:145], v[190:193], v[114:117]
	v_mfma_f32_16x16x32_bf16 v[110:113], v[150:153], v[190:193], v[110:113]
	v_mfma_f32_16x16x32_bf16 v[98:101], v[142:145], v[198:201], v[98:101]
	v_mfma_f32_16x16x32_bf16 v[94:97], v[150:153], v[198:201], v[94:97]
	v_mfma_f32_16x16x32_bf16 v[82:85], v[142:145], v[206:209], v[82:85]
	v_mfma_f32_16x16x32_bf16 v[78:81], v[150:153], v[206:209], v[78:81]
	v_mfma_f32_16x16x32_bf16 v[130:133], v[146:149], v[186:189], v[130:133]
	v_mfma_f32_16x16x32_bf16 v[126:129], v[154:157], v[186:189], v[126:129]
	v_mfma_f32_16x16x32_bf16 v[114:117], v[146:149], v[194:197], v[114:117]
	v_mfma_f32_16x16x32_bf16 v[110:113], v[154:157], v[194:197], v[110:113]
	v_mfma_f32_16x16x32_bf16 v[98:101], v[146:149], v[202:205], v[98:101]
	v_mfma_f32_16x16x32_bf16 v[94:97], v[154:157], v[202:205], v[94:97]
	v_mfma_f32_16x16x32_bf16 v[82:85], v[146:149], v[224:227], v[82:85]
	v_mfma_f32_16x16x32_bf16 v[78:81], v[154:157], v[224:227], v[78:81]
	s_setprio 0
	s_cmp_eq_u64 s[30:31], 0
	s_cbranch_scc1 .LBB0_1658
	s_setprio 1
	s_mov_b64 s[44:45], -1
	s_cmp_eq_u64 s[22:23], 0
	s_cbranch_scc1 .LBB0_1655
	v_mfma_f32_16x16x32_bf16 v[10:13], v[142:145], v[174:177], v[10:13]
	s_mov_b64 s[44:45], 0
	v_mfma_f32_16x16x32_bf16 v[6:9], v[150:153], v[174:177], v[6:9]
	v_mfma_f32_16x16x32_bf16 v[10:13], v[146:149], v[178:181], v[10:13]
	v_mfma_f32_16x16x32_bf16 v[6:9], v[154:157], v[178:181], v[6:9]

; #define PG8_STAGEX(b, gbase) do { if constexpr (XR) { if (lane < 16) __builtin_amdgcn_global_load_lds((const unsigned*)((const char*)(gbase) + voffX), (PG8_LAS unsigned*)(lds + XR_OFF + (b) * 2048 + wid * 256), 16, 0, 0); } } while (0)
; #define PG8_LDX(b) do { if constexpr (XR) { _Pragma("unroll") for (int k = 0; k < 2; ++k) Ax_[k] = *(const PG8_LAS bf16x8*)(lds + XR_OFF + (b) * 2048 + aoffx + k * 1024); } } while (0)
; #define PG8_MMAX() do { if constexpr (XR) { if (hasx) { __builtin_amdgcn_s_setprio(1); if (wr == 0) PG8_MMAX_(B0); else PG8_MMAX_(B1); __builtin_amdgcn_s_setprio(0); } } } while (0)
; #define PG8_WAIT_LOOP() do { if constexpr (XR) PG8_WAIT_V(9); else PG8_WAIT_V(8); } while (0)
; #define PG8_STAGE(bufoff, gbase, voff) do { _Pragma("unroll") for (int _i = 0; _i < 2; ++_i) \
;         __builtin_amdgcn_global_load_lds((const unsigned*)((const char*)(gbase) + (voff)[_i]), (PG8_LAS unsigned*)(lds + (bufoff) + ldsw + _i * 8192), 16, 0, 0); } while (0)
; #define PG8_LDA(dst, b, h) do { _Pragma("unroll") for (int m = 0; m < 4; ++m) _Pragma("unroll") for (int k = 0; k < 2; ++k) dst[m][k] = *(const PG8_LAS bf16x8*)(lds + PG8_SA(b, h) + aoff + m * 2048 + k * 1024); } while (0)
; template <class Epi, class Sched, bool ALIGN_EPI = false, bool SP2 = false, bool DRAIN = true, bool XR = false>
; __device__ __forceinline__ void gemm_phase(PG8_LAS unsigned char* lds, const Gemm g, const Sched& S, const Epi& E) {
;     ...
;             const bool last = (t == nt - 2);
;             const char* a1 = cA + PG8_KOA(t) + kstep;
;             const char* a2 = last ? nA + ka0 : cA + PG8_KOA(t + 2); const char* b2 = last ? nB + kb0 : cB + PG8_KOB(t + 2);
;             const char* x2 = XR ? (last ? nX + kx0 : cX + PG8_KOX(t + 2)) : nullptr; const char* x3 = XR ? x2 + kstep : nullptr;
;             const char* a3 = a2 + kstep; const char* b3 = b2 + kstep;
;             if (last && has_next) S.a_ready(nxt);
;             if constexpr (SP2) {
;             PG8_LDB(B0, 0, 0); PG8_LDB(B1, 0, 1); PG8_SCHED; PG8_LDA(At, 0, 0); PG8_LDX(0); PG8_STAGE(PG8_SA(1, 1), a1 + hstepA, voffA);
;             PG8_WAIT_LOOP(); PG8_WAIT_L(0); PG8_BAR; PG8_MMA(0, 0, At, B0); PG8_MMA(0, 1, At, B1); PG8_MMAX(); PG8_BAR; PG8_SCHED;
;             PG8_LDA(At, 0, 1); PG8_STAGE(PG8_SB(0, 0), b2, voffB); PG8_STAGE(PG8_SB(0, 1), b2 + hstep, voffB); PG8_STAGE(PG8_SA(0, 0), a2, voffA); PG8_STAGEX(0, x2);
.LBB0_1658:
	s_barrier
	v_cndmask_b32_e64 v2, 0, 1, s[30:31]
	v_cmp_ne_u32_e64 s[6:7], 1, v2
	v_cndmask_b32_e64 v2, 0, 1, s[22:23]
	v_cmp_ne_u32_e64 s[0:1], 1, v2
	s_add_i32 s46, s46, 2
	s_and_b32 s44, s46, s59
	s_lshr_b32 s84, s44, 2
	s_lshl_b32 s36, s44, 7
	s_lshl_b64 s[46:47], s[84:85], 17
	s_and_b32 s36, s36, 0x100
	s_add_u32 s45, s40, s46
	s_addc_u32 s46, s41, s47
	s_add_u32 s36, s45, s36
	s_mov_b32 s45, s85
	s_addc_u32 s46, s46, 0
	s_lshl_b64 s[44:45], s[44:45], 7
	s_add_u32 vcc_lo, s34, s44
	s_addc_u32 vcc_hi, s35, s45
	s_add_u32 s12, s42, s44
	s_addc_u32 s13, s43, s45
	s_cmp_eq_u32 s82, s89
	s_cselect_b32 s45, s39, s46
	s_cselect_b32 s44, s93, s36
	s_cselect_b32 s47, s90, s13
	s_cselect_b32 s46, s97, s12
	s_cselect_b32 vcc_hi, s96, vcc_hi
	s_cselect_b32 vcc_lo, s50, vcc_lo
	s_mov_b32 m0, s64
	v_lshl_add_u64 v[224:225], vcc, 0, v[216:217]
	v_lshl_add_u64 v[226:227], vcc, 0, v[220:221]
	s_add_u32 vcc_lo, vcc_lo, s8
	ds_read_b128 v[198:201], v249 offset:16384
	ds_read_b128 v[202:205], v249 offset:17408
	ds_read_b128 v[190:193], v249 offset:18432
	ds_read_b128 v[194:197], v249 offset:19456
	ds_read_b128 v[182:185], v249 offset:20480
	ds_read_b128 v[186:189], v249 offset:21504
	ds_read_b128 v[174:177], v249 offset:22528
	ds_read_b128 v[178:181], v249 offset:23552
	global_load_lds_dwordx4 v[224:225], off
	s_mov_b32 m0, s65
	s_addc_u32 vcc_hi, vcc_hi, s9
	global_load_lds_dwordx4 v[226:227], off
	v_lshl_add_u64 v[228:229], vcc, 0, v[216:217]
	s_mov_b32 m0, s67
	v_lshl_add_u64 v[230:231], vcc, 0, v[220:221]
	global_load_lds_dwordx4 v[228:229], off
	s_mov_b32 m0, s68
	v_lshl_add_u64 v[232:233], s[44:45], 0, v[214:215]
	global_load_lds_dwordx4 v[230:231], off
	s_mov_b32 m0, s63
	v_lshl_add_u64 v[234:235], s[44:45], 0, v[218:219]
	global_load_lds_dwordx4 v[232:233], off
	s_mov_b32 m0, s69
	v_lshl_add_u64 v[4:5], s[46:47], 0, v[222:223]
	global_load_lds_dwordx4 v[234:235], off
	s_and_saveexec_b64 s[46:47], s[2:3]
	s_cbranch_execz .LBB0_1660
	s_add_i32 s12, s60, 0
	s_add_i32 m0, s12, 0x22400
	s_nop 0
	global_load_lds_dwordx4 v[4:5], off

; #define PG8_LDX(b) do { if constexpr (XR) { _Pragma("unroll") for (int k = 0; k < 2; ++k) Ax_[k] = *(const PG8_LAS bf16x8*)(lds + XR_OFF + (b) * 2048 + aoffx + k * 1024); } } while (0)
; #define PG8_MMAX() do { if constexpr (XR) { if (hasx) { __builtin_amdgcn_s_setprio(1); if (wr == 0) PG8_MMAX_(B0); else PG8_MMAX_(B1); __builtin_amdgcn_s_setprio(0); } } } while (0)
; #define PG8_WAIT_LOOP() do { if constexpr (XR) PG8_WAIT_V(9); else PG8_WAIT_V(8); } while (0)
; #define PG8_STAGE(bufoff, gbase, voff) do { _Pragma("unroll") for (int _i = 0; _i < 2; ++_i) \
;         __builtin_amdgcn_global_load_lds((const unsigned*)((const char*)(gbase) + (voff)[_i]), (PG8_LAS unsigned*)(lds + (bufoff) + ldsw + _i * 8192), 16, 0, 0); } while (0)
; #define PG8_LDA(dst, b, h) do { _Pragma("unroll") for (int m = 0; m < 4; ++m) _Pragma("unroll") for (int k = 0; k < 2; ++k) dst[m][k] = *(const PG8_LAS bf16x8*)(lds + PG8_SA(b, h) + aoff + m * 2048 + k * 1024); } while (0)
; #define PG8_LDB(dst, b, h) do { _Pragma("unroll") for (int n = 0; n < 2; ++n) _Pragma("unroll") for (int k = 0; k < 2; ++k) dst[n][k] = *(const PG8_LAS bf16x8*)(lds + PG8_SB(b, h) + boff + n * 2048 + k * 1024); } while (0)
; #define PG8_MMA(ai, bj, At, Bt) do { __builtin_amdgcn_s_setprio(1); _Pragma("unroll") for (int m = 0; m < 4; ++m) _Pragma("unroll") for (int n = 0; n < 2; ++n) _Pragma("unroll") for (int k = 0; k < 2; ++k) \
;         acc[ai][bj][m][n] = __builtin_amdgcn_mfma_f32_16x16x32_bf16(Bt[n][k], At[m][k], acc[ai][bj][m][n], 0, 0, 0); __builtin_amdgcn_s_setprio(0); } while (0)
; #define PG8_WAIT_L(n) asm volatile("s_waitcnt lgkmcnt(" #n ")" ::: "memory")
; #define PG8_BAR __builtin_amdgcn_s_barrier()
; #define PG8_SCHED __builtin_amdgcn_sched_barrier(0)
; template <class Epi, class Sched, bool ALIGN_EPI = false, bool SP2 = false, bool DRAIN = true, bool XR = false>
; __device__ __forceinline__ void gemm_phase(PG8_LAS unsigned char* lds, const Gemm g, const Sched& S, const Epi& E) {
;     ...
;             PG8_LDB(B0, 0, 0); PG8_LDB(B1, 0, 1); PG8_SCHED; PG8_LDA(At, 0, 0); PG8_LDX(0); PG8_STAGE(PG8_SA(1, 1), a1 + hstepA, voffA);
;             PG8_WAIT_LOOP(); PG8_WAIT_L(0); PG8_BAR; PG8_MMA(0, 0, At, B0); PG8_MMA(0, 1, At, B1); PG8_MMAX(); PG8_BAR; PG8_SCHED;
.LBB0_1856:
	v_add_u32_e32 v2, 0x10000, v237
	s_add_i32 s56, s88, s45
	ds_read_b128 v[158:161], v2
	ds_read_b128 v[162:165], v2 offset:1024
	ds_read_b128 v[166:169], v2 offset:2048
	ds_read_b128 v[170:173], v2 offset:3072
	v_add_u32_e32 v2, 0x14000, v237
	s_and_b32 s8, s56, s67
	ds_read_b128 v[142:145], v2
	ds_read_b128 v[146:149], v2 offset:1024
	ds_read_b128 v[150:153], v2 offset:2048
	ds_read_b128 v[154:157], v2 offset:3072
	s_lshr_b32 s84, s8, 2
	s_lshl_b32 s8, s8, 7
	s_lshl_b64 s[0:1], s[84:85], 9
	s_and_b32 s8, s8, 0x100
	s_add_u32 s0, s24, s0
	s_addc_u32 s1, s25, s1
	s_add_u32 s0, s0, s8
	s_addc_u32 s1, s1, 0
	s_add_u32 s0, s0, s18
	s_addc_u32 s1, s1, s19
	v_lshl_add_u64 v[4:5], s[0:1], 0, v[214:215]
	v_add_u32_e32 v2, 0x22400, v239
	v_lshl_add_u64 v[4:5], v[4:5], 0, s[86:87]
	s_add_i32 m0, s72, 0xc000
	ds_read_b128 v[182:185], v238
	ds_read_b128 v[186:189], v238 offset:1024
	ds_read_b128 v[190:193], v238 offset:2048
	ds_read_b128 v[194:197], v238 offset:3072
	ds_read_b128 v[198:201], v238 offset:4096
	ds_read_b128 v[202:205], v238 offset:5120
	ds_read_b128 v[206:209], v238 offset:6144
	ds_read_b128 v[224:227], v238 offset:7168
	ds_read_b128 v[174:177], v2
	ds_read_b128 v[178:181], v2 offset:1024
	global_load_lds_dwordx4 v[4:5], off
	v_lshl_add_u64 v[4:5], s[0:1], 0, v[218:219]
	v_lshl_add_u64 v[4:5], v[4:5], 0, s[86:87]
	s_add_i32 m0, s72, 0xe000
	s_nop 0
	global_load_lds_dwordx4 v[4:5], off
	s_waitcnt vmcnt(9)
	s_waitcnt lgkmcnt(0)
	s_setprio 1
	s_barrier
	v_mfma_f32_16x16x32_bf16 v[138:141], v[158:161], v[182:185], v[138:141]
	v_mfma_f32_16x16x32_bf16 v[134:137], v[166:169], v[182:185], v[134:137]
	v_mfma_f32_16x16x32_bf16 v[130:133], v[158:161], v[190:193], v[130:133]
	v_mfma_f32_16x16x32_bf16 v[126:129], v[166:169], v[190:193], v[126:129]
	v_mfma_f32_16x16x32_bf16 v[122:125], v[158:161], v[198:201], v[122:125]
	v_mfma_f32_16x16x32_bf16 v[118:121], v[166:169], v[198:201], v[118:121]
	v_mfma_f32_16x16x32_bf16 v[114:117], v[158:161], v[206:209], v[114:117]
	v_mfma_f32_16x16x32_bf16 v[110:113], v[166:169], v[206:209], v[110:113]
	v_mfma_f32_16x16x32_bf16 v[138:141], v[162:165], v[186:189], v[138:141]
	v_mfma_f32_16x16x32_bf16 v[134:137], v[170:173], v[186:189], v[134:137]
	v_mfma_f32_16x16x32_bf16 v[130:133], v[162:165], v[194:197], v[130:133]
	v_mfma_f32_16x16x32_bf16 v[126:129], v[170:173], v[194:197], v[126:129]
	v_mfma_f32_16x16x32_bf16 v[122:125], v[162:165], v[202:205], v[122:125]
	v_mfma_f32_16x16x32_bf16 v[118:121], v[170:173], v[202:205], v[118:121]
	v_mfma_f32_16x16x32_bf16 v[114:117], v[162:165], v[224:227], v[114:117]
	v_mfma_f32_16x16x32_bf16 v[110:113], v[170:173], v[224:227], v[110:113]
	v_mfma_f32_16x16x32_bf16 v[106:109], v[142:145], v[182:185], v[106:109]
	v_mfma_f32_16x16x32_bf16 v[102:105], v[150:153], v[182:185], v[102:105]
	v_mfma_f32_16x16x32_bf16 v[98:101], v[142:145], v[190:193], v[98:101]
	v_mfma_f32_16x16x32_bf16 v[94:97], v[150:153], v[190:193], v[94:97]
	v_mfma_f32_16x16x32_bf16 v[90:93], v[142:145], v[198:201], v[90:93]
	v_mfma_f32_16x16x32_bf16 v[86:89], v[150:153], v[198:201], v[86:89]
	v_mfma_f32_16x16x32_bf16 v[82:85], v[142:145], v[206:209], v[82:85]
	v_mfma_f32_16x16x32_bf16 v[78:81], v[150:153], v[206:209], v[78:81]
	v_mfma_f32_16x16x32_bf16 v[106:109], v[146:149], v[186:189], v[106:109]
	v_mfma_f32_16x16x32_bf16 v[102:105], v[154:157], v[186:189], v[102:105]
	v_mfma_f32_16x16x32_bf16 v[98:101], v[146:149], v[194:197], v[98:101]
	v_mfma_f32_16x16x32_bf16 v[94:97], v[154:157], v[194:197], v[94:97]
	v_mfma_f32_16x16x32_bf16 v[90:93], v[146:149], v[202:205], v[90:93]
	v_mfma_f32_16x16x32_bf16 v[86:89], v[154:157], v[202:205], v[86:89]
	v_mfma_f32_16x16x32_bf16 v[82:85], v[146:149], v[224:227], v[82:85]
	v_mfma_f32_16x16x32_bf16 v[78:81], v[154:157], v[224:227], v[78:81]
	s_setprio 0
	s_cmp_eq_u64 s[40:41], 0
	s_cbranch_scc1 .LBB0_1862
	s_setprio 1
	s_mov_b64 s[54:55], -1
	s_cmp_eq_u64 s[46:47], 0
	s_cbranch_scc1 .LBB0_1859
	v_mfma_f32_16x16x32_bf16 v[10:13], v[142:145], v[174:177], v[10:13]
	s_mov_b64 s[54:55], 0
	v_mfma_f32_16x16x32_bf16 v[6:9], v[150:153], v[174:177], v[6:9]
	v_mfma_f32_16x16x32_bf16 v[10:13], v[146:149], v[178:181], v[10:13]
	v_mfma_f32_16x16x32_bf16 v[6:9], v[154:157], v[178:181], v[6:9]

; #define PG8_STAGEX(b, gbase) do { if constexpr (XR) { if (lane < 16) __builtin_amdgcn_global_load_lds((const unsigned*)((const char*)(gbase) + voffX), (PG8_LAS unsigned*)(lds + XR_OFF + (b) * 2048 + wid * 256), 16, 0, 0); } } while (0)
; #define PG8_LDX(b) do { if constexpr (XR) { _Pragma("unroll") for (int k = 0; k < 2; ++k) Ax_[k] = *(const PG8_LAS bf16x8*)(lds + XR_OFF + (b) * 2048 + aoffx + k * 1024); } } while (0)
; #define PG8_MMAX() do { if constexpr (XR) { if (hasx) { __builtin_amdgcn_s_setprio(1); if (wr == 0) PG8_MMAX_(B0); else PG8_MMAX_(B1); __builtin_amdgcn_s_setprio(0); } } } while (0)
; #define PG8_WAIT_LOOP() do { if constexpr (XR) PG8_WAIT_V(9); else PG8_WAIT_V(8); } while (0)
; #define PG8_STAGE(bufoff, gbase, voff) do { _Pragma("unroll") for (int _i = 0; _i < 2; ++_i) \
;         __builtin_amdgcn_global_load_lds((const unsigned*)((const char*)(gbase) + (voff)[_i]), (PG8_LAS unsigned*)(lds + (bufoff) + ldsw + _i * 8192), 16, 0, 0); } while (0)
; #define PG8_LDA(dst, b, h) do { _Pragma("unroll") for (int m = 0; m < 4; ++m) _Pragma("unroll") for (int k = 0; k < 2; ++k) dst[m][k] = *(const PG8_LAS bf16x8*)(lds + PG8_SA(b, h) + aoff + m * 2048 + k * 1024); } while (0)
; template <class Epi, class Sched, bool ALIGN_EPI = false, bool SP2 = false, bool DRAIN = true, bool XR = false>
; __device__ __forceinline__ void gemm_phase(PG8_LAS unsigned char* lds, const Gemm g, const Sched& S, const Epi& E) {
;     ...
;             const bool last = (t == nt - 2);
;             const char* a1 = cA + PG8_KOA(t) + kstep;
;             const char* a2 = last ? nA + ka0 : cA + PG8_KOA(t + 2); const char* b2 = last ? nB + kb0 : cB + PG8_KOB(t + 2);
;             const char* x2 = XR ? (last ? nX + kx0 : cX + PG8_KOX(t + 2)) : nullptr; const char* x3 = XR ? x2 + kstep : nullptr;
;             const char* a3 = a2 + kstep; const char* b3 = b2 + kstep;
;             if (last && has_next) S.a_ready(nxt);
;             if constexpr (SP2) {
;             PG8_LDB(B0, 0, 0); PG8_LDB(B1, 0, 1); PG8_SCHED; PG8_LDA(At, 0, 0); PG8_LDX(0); PG8_STAGE(PG8_SA(1, 1), a1 + hstepA, voffA);
;             PG8_WAIT_LOOP(); PG8_WAIT_L(0); PG8_BAR; PG8_MMA(0, 0, At, B0); PG8_MMA(0, 1, At, B1); PG8_MMAX(); PG8_BAR; PG8_SCHED;
;             PG8_LDA(At, 0, 1); PG8_STAGE(PG8_SB(0, 0), b2, voffB); PG8_STAGE(PG8_SB(0, 1), b2 + hstep, voffB); PG8_STAGE(PG8_SA(0, 0), a2, voffA); PG8_STAGEX(0, x2);
.LBB0_1862:
	s_barrier
	v_cndmask_b32_e64 v2, 0, 1, s[40:41]
	v_cmp_ne_u32_e64 s[8:9], 1, v2
	v_cndmask_b32_e64 v2, 0, 1, s[46:47]
	v_cmp_ne_u32_e64 s[0:1], 1, v2
	s_add_i32 s56, s56, 2
	s_and_b32 s54, s56, s67
	s_lshr_b32 s84, s54, 2
	s_lshl_b32 s36, s54, 7
	s_lshl_b64 s[56:57], s[84:85], 9
	s_and_b32 s36, s36, 0x100
	s_add_u32 s55, s24, s56
	s_addc_u32 s56, s25, s57
	s_add_u32 s36, s55, s36
	s_mov_b32 s55, s85
	s_addc_u32 s56, s56, 0
	s_lshl_b64 s[54:55], s[54:55], 7
	s_add_u32 vcc_lo, s22, s54
	s_addc_u32 vcc_hi, s23, s55
	s_add_u32 s70, s28, s54
	s_addc_u32 s57, s29, s55
	s_cmp_eq_u32 s63, s45
	s_cselect_b32 s55, s59, s56
	s_cselect_b32 s54, s58, s36
	s_cselect_b32 s57, s44, s57
	s_cselect_b32 s56, s43, s70
	s_cselect_b32 vcc_hi, s42, vcc_hi
	s_cselect_b32 vcc_lo, s78, vcc_lo
	s_mov_b32 m0, s73
	v_lshl_add_u64 v[224:225], vcc, 0, v[216:217]
	v_lshl_add_u64 v[226:227], vcc, 0, v[220:221]
	s_add_u32 vcc_lo, vcc_lo, s18
	ds_read_b128 v[198:201], v238 offset:16384
	ds_read_b128 v[202:205], v238 offset:17408
	ds_read_b128 v[190:193], v238 offset:18432
	ds_read_b128 v[194:197], v238 offset:19456
	ds_read_b128 v[182:185], v238 offset:20480
	ds_read_b128 v[186:189], v238 offset:21504
	ds_read_b128 v[174:177], v238 offset:22528
	ds_read_b128 v[178:181], v238 offset:23552
	global_load_lds_dwordx4 v[224:225], off
	s_mov_b32 m0, s74
	s_addc_u32 vcc_hi, vcc_hi, s19
	global_load_lds_dwordx4 v[226:227], off
	v_lshl_add_u64 v[228:229], vcc, 0, v[216:217]
	s_mov_b32 m0, s75
	v_lshl_add_u64 v[230:231], vcc, 0, v[220:221]
	global_load_lds_dwordx4 v[228:229], off
	s_mov_b32 m0, s76
	v_lshl_add_u64 v[232:233], s[54:55], 0, v[214:215]
	global_load_lds_dwordx4 v[230:231], off
	s_mov_b32 m0, s72
	v_lshl_add_u64 v[234:235], s[54:55], 0, v[218:219]
	global_load_lds_dwordx4 v[232:233], off
	s_mov_b32 m0, s77
	v_lshl_add_u64 v[4:5], s[56:57], 0, v[222:223]
	global_load_lds_dwordx4 v[234:235], off
	s_and_saveexec_b64 s[56:57], s[2:3]
	s_cbranch_execz .LBB0_1864
	s_add_i32 s36, s68, 0
	s_add_i32 m0, s36, 0x22400
	s_nop 0
	global_load_lds_dwordx4 v[4:5], off
